# grid barrier v2: first arriver of each XCC is its leader (polls the XCC counter, writes back, arrives on TOP without a returning atomic); every workgroup polls TOP directly (no per-XCC generation hop)
# baseline (speedup 1.0000x reference)
.Lxb0_go:
	v_add_u32_e32 v246, 0x1400, v245
	global_atomic_add v248, v246, v247, s[60:61] sc0
	buffer_inv sc1
	v_add_u32_e32 v249, 1, v244
	ds_write_b32 v241, v249 offset:8
	v_mul_lo_u32 v250, v244, v242
	v_mul_lo_u32 v251, v249, v243
	v_mul_lo_u32 v253, v249, v242
	v_mov_b32_e32 v252, 0
	v_mov_b32_e32 v254, 0x3400
	s_waitcnt vmcnt(1)
	v_cmp_eq_u32_e32 vcc, v248, v250
	s_cbranch_vccz .Lxb0_wait
.Lxb0_lpoll:
	global_load_dword v248, v246, s[60:61] sc1
	v_add_u32_e32 v252, 1, v252
	s_waitcnt vmcnt(0)
	v_cmp_ge_u32_e32 vcc, v248, v253
	s_cbranch_vccnz .Lxb0_ldone
	v_cmp_gt_u32_e32 vcc, 0x100000, v252
	s_cbranch_vccz .Lxb0_ldone
	s_branch .Lxb0_lpoll
.Lxb0_ldone:
	buffer_wbl2 sc1
	s_waitcnt vmcnt(0)
	global_atomic_add v254, v247, s[60:61]
.Lxb0_wait:
	global_load_dword v248, v254, s[60:61] sc1
	v_add_u32_e32 v252, 1, v252
	s_waitcnt vmcnt(0)
	v_cmp_ge_u32_e32 vcc, v248, v251
	s_cbranch_vccnz .Lxb0_wdone
	v_cmp_gt_u32_e32 vcc, 0x200000, v252
	s_cbranch_vccz .Lxb0_wdone
	s_sleep 1
	s_branch .Lxb0_wait

.Lxb2_ldone:
	global_atomic_add v254, v247, s[60:61]
